# SSD loop: previous chunk's y stores issued after the conv-stage weight waits (phase-neutral), on top of resid-GEMM epilogue alignment
# baseline (speedup 1.0000x reference)
; #define wt16(p, v) wt16b(WSB, (p), (v))
; #define LAS __attribute__((address_space(3)))
; __device__ __forceinline__ void ssd_item(CArgs a, int layer, int item, LAS unsigned char* lds) {
;     ...
;         const int c = dir ? 15 - cc : cc; const int t0 = c * 128;
;         const float dtv = pdt;
;         if (tid < 128) v_dA[tid] = dtv * Aneg;
;         __syncthreads();
;         if (cc > 0) {
; #pragma unroll
;             for (int i = 0; i < 2; ++i) { const int c2 = tid + 512 * i, row = c2 >> 3, part = c2 & 7;
;                 wt16(yout + (size_t)(tprev + row) * ystr + part * 8, *(const LAS u32x4*)(Bw + row * YS_LD + part * 8)); }
.LBB0_196:
	s_waitcnt vmcnt(20)
	v_mov_b32_e32 v123, v244
	s_nop 0
	v_readfirstlane_b32 s34, v123
	v_cmp_gt_i32_e32 vcc, s33, v123
	s_and_saveexec_b64 s[2:3], vcc
	v_lshl_add_u32 v18, v123, 2, 0
	v_mul_f32_e32 v0, v191, v192
	v_add_u32_e32 v18, 0x22000, v18
	ds_write_b32 v18, v0
	s_or_b64 exec, exec, s[2:3]
	s_cmp_eq_u32 s90, 0
	s_waitcnt lgkmcnt(0)
	s_barrier
	s_cbranch_scc1 .LBB0_200
	v_ashrrev_i32_e32 v18, 3, v123
	v_lshlrev_b32_e32 v0, 4, v123
	v_add_u32_e32 v19, s27, v18
	v_and_b32_e32 v22, 0x70, v0
	v_lshlrev_b32_e32 v19, s12, v19
	v_add_u32_e32 v0, 0, v22
	v_lshlrev_b32_e32 v19, 1, v19
	v_add3_u32 v23, s13, v19, v22
	v_mad_u64_u32 v[18:19], s[2:3], v18, s82, v[0:1]
	ds_read_b128 v[222:225], v18 offset:34816
	v_subrev_u32_e32 v230, s60, v23
	s_waitcnt lgkmcnt(0)
	s_nop 1
	v_add_u32_e32 v18, 0x200, v123
	v_ashrrev_i32_e32 v18, 3, v18
	v_add_u32_e32 v19, s27, v18
	v_lshlrev_b32_e32 v19, s12, v19
	v_lshlrev_b32_e32 v19, 1, v19
	v_add3_u32 v22, s13, v19, v22
	v_mad_u64_u32 v[18:19], s[2:3], v18, s82, v[0:1]
	ds_read_b128 v[226:229], v18 offset:34816
	v_subrev_u32_e32 v231, s60, v22
	s_waitcnt lgkmcnt(0)

; __device__ __forceinline__ unsigned cvt_pk_bf16(float lo, float hi) { f32x2_t v = {lo, hi}; bf16x2_t b = __builtin_convertvector(v, bf16x2_t); return __builtin_bit_cast(unsigned, b); }
; #define LAS __attribute__((address_space(3)))
; __device__ __forceinline__ void ssd_item(CArgs a, int layer, int item, LAS unsigned char* lds) {
;     ...
;         etot = vec[640];
;         {
;             const int cg8 = tid & 15, rb = tid >> 4, l0 = rb * 4;
;             float o[4][8];
;             float wg[4];
; #pragma unroll
;             for (int r = 0; r < 4; ++r) { *(LAS u32x4*)(Cm + (l0 + r) * SS_LD + cg8 * 8) = pc[r]; *(LAS u32x4*)(Bw + (l0 + r) * SS_LD + cg8 * 8) = pb[r]; unpack8(pb[r], o[r]); wg[r] = v_wgt[l0 + r]; }
; #pragma unroll
;             for (int e = 0; e < 8; ++e) { u32x2 w; w.x = cvt_pk_bf16(o[0][e] * wg[0], o[1][e] * wg[1]); w.y = cvt_pk_bf16(o[2][e] * wg[2], o[3][e] * wg[3]);
;                 *(LAS u32x2*)(Bt + (cg8 * 8 + e) * SS_LD + l0) = w; }
;             const int xg = tid & 7, xr = tid >> 3, xl0 = xr * 2;
;             float ox[2][8];
;             {
;                 const int c0 = hd * 64 + xg * 8;
;                 float bias[8];
;                 { const f32x4 a0 = *(const f32x4*)(cb + c0), a1 = *(const f32x4*)(cb + c0 + 4);
;                   bias[0] = a0[0]; bias[1] = a0[1]; bias[2] = a0[2]; bias[3] = a0[3]; bias[4] = a1[0]; bias[5] = a1[1]; bias[6] = a1[2]; bias[7] = a1[3]; }
; #pragma unroll
;                 for (int e = 0; e < 8; ++e) { ox[0][e] = bias[e]; ox[1][e] = bias[e]; }
; #pragma unroll
;                 for (int k = 0; k < 5; ++k) {
;                     const f32x4 a0 = *(const f32x4*)(cw + k * 1536 + c0), a1 = *(const f32x4*)(cw + k * 1536 + c0 + 4);
;                     const float w[8] = {a0[0], a0[1], a0[2], a0[3], a1[0], a1[1], a1[2], a1[3]};
;                     float i0[8], i1[8]; unpack8(px[k], i0); unpack8(px[k + 1], i1);
; #pragma unroll
;                     for (int e = 0; e < 8; ++e) { ox[0][e] += w[e] * i0[e]; ox[1][e] += w[e] * i1[e]; }
;                 }
.LBB0_203:
	s_or_b64 exec, exec, s[26:27]
	v_lshlrev_b32_e32 v28, 3, v123
	v_mov_b32_e32 v0, s76
	v_ashrrev_i32_e32 v127, 2, v123
	v_and_b32_e32 v26, 0x78, v28
	s_waitcnt lgkmcnt(0)
	s_barrier
	ds_read_b32 v122, v0
	v_and_b32_e32 v22, -4, v127
	v_lshl_add_u32 v0, v26, 1, 0
	v_mad_u64_u32 v[18:19], s[2:3], v22, s84, v[0:1]
	s_add_i32 s26, 0, 0x22600
	s_waitcnt vmcnt(12)
	ds_write_b128 v18, v[54:57]
	ds_write_b128 v18, v[50:53] offset:34816
	v_lshl_add_u32 v19, v22, 2, s26
	v_or_b32_e32 v23, 3, v127
	v_lshlrev_b32_e32 v27, 1, v22
	ds_read_b32 v22, v19
	ds_write_b128 v18, v[62:65] offset:272
	ds_write_b128 v18, v[58:61] offset:35088
	v_mad_u64_u32 v[20:21], s[2:3], v23, s84, v[0:1]
	v_lshl_add_u32 v0, v23, 2, s26
	ds_read_b32 v23, v19 offset:4
	ds_write_b128 v18, v[70:73] offset:544
	ds_write_b128 v18, v[66:69] offset:35360
	ds_read_b32 v18, v19 offset:8
	ds_write_b128 v20, v[78:81]
	ds_write_b128 v20, v[74:77] offset:34816
	ds_read_b32 v19, v0
	v_lshlrev_b32_e32 v25, 16, v58
	v_lshlrev_b32_e32 v24, 16, v50
	s_waitcnt lgkmcnt(6)
	v_pk_mul_f32 v[20:21], v[22:23], v[24:25]
	v_lshlrev_b32_e32 v25, 16, v74
	v_lshlrev_b32_e32 v24, 16, v66
	s_waitcnt lgkmcnt(0)
	v_pk_mul_f32 v[24:25], v[18:19], v[24:25]
	v_mul_u32_u24_e32 v0, 0x110, v26
	v_cvt_pk_bf16_f32 v20, v20, v21
	v_cvt_pk_bf16_f32 v21, v24, v25
	v_add3_u32 v0, s77, v27, v0
	v_and_b32_e32 v25, 0xffff0000, v58
	v_and_b32_e32 v24, 0xffff0000, v50
	v_and_b32_e32 v27, 0xffff0000, v74
	v_and_b32_e32 v26, 0xffff0000, v66
	v_pk_mul_f32 v[24:25], v[22:23], v[24:25]
	v_pk_mul_f32 v[26:27], v[18:19], v[26:27]
	v_cvt_pk_bf16_f32 v24, v24, v25
	v_cvt_pk_bf16_f32 v25, v26, v27
	ds_write2_b64 v0, v[20:21], v[24:25] offset1:34
	v_lshlrev_b32_e32 v21, 16, v59
	v_lshlrev_b32_e32 v20, 16, v51
	v_lshlrev_b32_e32 v25, 16, v75
	v_lshlrev_b32_e32 v24, 16, v67
	v_pk_mul_f32 v[20:21], v[22:23], v[20:21]
	v_pk_mul_f32 v[24:25], v[18:19], v[24:25]
	v_cvt_pk_bf16_f32 v20, v20, v21
	v_cvt_pk_bf16_f32 v21, v24, v25
	v_and_b32_e32 v25, 0xffff0000, v59
	v_and_b32_e32 v24, 0xffff0000, v51
	v_and_b32_e32 v27, 0xffff0000, v75
	v_and_b32_e32 v26, 0xffff0000, v67
	v_pk_mul_f32 v[24:25], v[22:23], v[24:25]
	v_pk_mul_f32 v[26:27], v[18:19], v[26:27]
	v_cvt_pk_bf16_f32 v24, v24, v25
	v_cvt_pk_bf16_f32 v25, v26, v27
	ds_write2_b64 v0, v[20:21], v[24:25] offset0:68 offset1:102
	v_lshlrev_b32_e32 v21, 16, v60
	v_lshlrev_b32_e32 v20, 16, v52
	v_lshlrev_b32_e32 v25, 16, v76
	v_lshlrev_b32_e32 v24, 16, v68
	v_pk_mul_f32 v[20:21], v[22:23], v[20:21]
	v_pk_mul_f32 v[24:25], v[18:19], v[24:25]
	v_cvt_pk_bf16_f32 v20, v20, v21
	v_cvt_pk_bf16_f32 v21, v24, v25
	v_and_b32_e32 v25, 0xffff0000, v60
	v_and_b32_e32 v24, 0xffff0000, v52
	v_and_b32_e32 v27, 0xffff0000, v76
	v_and_b32_e32 v26, 0xffff0000, v68
	v_pk_mul_f32 v[24:25], v[22:23], v[24:25]
	v_pk_mul_f32 v[26:27], v[18:19], v[26:27]
	v_cvt_pk_bf16_f32 v24, v24, v25
	v_cvt_pk_bf16_f32 v25, v26, v27
	ds_write2_b64 v0, v[20:21], v[24:25] offset0:136 offset1:170
	v_lshlrev_b32_e32 v21, 16, v61
	v_lshlrev_b32_e32 v20, 16, v53
	v_lshlrev_b32_e32 v25, 16, v77
	v_lshlrev_b32_e32 v24, 16, v69
	v_pk_mul_f32 v[20:21], v[22:23], v[20:21]
	v_pk_mul_f32 v[24:25], v[18:19], v[24:25]
	v_cvt_pk_bf16_f32 v20, v20, v21
	v_cvt_pk_bf16_f32 v21, v24, v25
	v_and_b32_e32 v25, 0xffff0000, v61
	v_and_b32_e32 v24, 0xffff0000, v53
	v_pk_mul_f32 v[22:23], v[22:23], v[24:25]
	v_and_b32_e32 v25, 0xffff0000, v77
	v_and_b32_e32 v24, 0xffff0000, v69
	v_pk_mul_f32 v[18:19], v[18:19], v[24:25]
	v_cvt_pk_bf16_f32 v22, v22, v23
	v_cvt_pk_bf16_f32 v23, v18, v19
	v_and_b32_e32 v128, 56, v28
	ds_write2_b64 v0, v[20:21], v[22:23] offset0:204 offset1:238
	v_or_b32_e32 v0, s89, v128
	v_lshlrev_b32_e32 v0, 2, v0
	v_lshl_add_u64 v[38:39], s[18:19], 0, v[0:1]
	v_add_co_u32_e32 v28, vcc, s74, v38
	global_load_dwordx4 v[18:21], v0, s[20:21] offset:16
	global_load_dwordx4 v[42:45], v0, s[20:21]
	v_addc_co_u32_e32 v29, vcc, 0, v39, vcc
	v_add_co_u32_e32 v32, vcc, s97, v38
	global_load_dwordx4 v[22:25], v0, s[18:19] offset:16
	global_load_dwordx4 v[46:49], v0, s[18:19]
	v_addc_co_u32_e32 v33, vcc, 0, v39, vcc
	v_lshl_add_u64 v[26:27], v[38:39], 0, s[68:69]
	v_add_co_u32_e32 v36, vcc, s65, v38
	global_load_dwordx4 v[106:109], v[28:29], off offset:2048
	s_nop 0
	global_load_dwordx4 v[26:29], v[26:27], off offset:16
	v_lshl_add_u64 v[30:31], v[38:39], 0, s[86:87]
	v_addc_co_u32_e32 v37, vcc, 0, v39, vcc
	global_load_dwordx4 v[110:113], v[32:33], off
	s_nop 0
	global_load_dwordx4 v[30:33], v[30:31], off offset:16
	v_lshl_add_u64 v[34:35], v[38:39], 0, s[72:73]
	v_lshl_add_u64 v[40:41], v[38:39], 0, s[0:1]
	v_add_co_u32_e32 v38, vcc, s95, v38
	global_load_dwordx4 v[114:117], v[36:37], off offset:2048
	s_nop 0
	global_load_dwordx4 v[34:37], v[34:35], off offset:16
	v_addc_co_u32_e32 v39, vcc, 0, v39, vcc
	global_load_dwordx4 v[118:121], v[38:39], off
	s_nop 0
	global_load_dwordx4 v[38:41], v[40:41], off offset:16
	s_waitcnt vmcnt(12)
	v_lshlrev_b32_e32 v124, 16, v84
	v_lshlrev_b32_e32 v125, 16, v88
	v_lshlrev_b32_e32 v131, 16, v92
	v_mov_b32_e32 v130, v125
	v_lshlrev_b32_e32 v133, 16, v96
	v_mov_b32_e32 v132, v131
	v_lshlrev_b32_e32 v135, 16, v100
	v_mov_b32_e32 v134, v133
	s_add_i32 s26, s90, 1
	s_cmp_eq_u32 s10, -1
	s_waitcnt vmcnt(8)
	v_pk_fma_f32 v[124:125], v[46:47], v[124:125], v[42:43] op_sel_hi:[0,1,0]
	s_waitcnt vmcnt(7)
	v_pk_fma_f32 v[124:125], v[106:107], v[130:131], v[124:125] op_sel_hi:[0,1,1]
	v_lshlrev_b32_e32 v131, 16, v104
	v_mov_b32_e32 v130, v135
	s_waitcnt vmcnt(5)
	v_pk_fma_f32 v[124:125], v[110:111], v[132:133], v[124:125] op_sel_hi:[0,1,1]
	v_and_b32_e32 v133, 0xffff0000, v92
	s_waitcnt vmcnt(3)
; __device__ __forceinline__ float silu_f(float x) { return x * __builtin_amdgcn_rcpf(1.f + __expf(-x)); }
; __device__ __forceinline__ void ssd_item(CArgs a, int layer, int item, LAS unsigned char* lds) {
;     ...
;                 for (int k = 0; k < 5; ++k) {
;                     const f32x4 a0 = *(const f32x4*)(cw + k * 1536 + c0), a1 = *(const f32x4*)(cw + k * 1536 + c0 + 4);
;                     const float w[8] = {a0[0], a0[1], a0[2], a0[3], a1[0], a1[1], a1[2], a1[3]};
;                     float i0[8], i1[8]; unpack8(px[k], i0); unpack8(px[k + 1], i1);
; #pragma unroll
;                     for (int e = 0; e < 8; ++e) { ox[0][e] += w[e] * i0[e]; ox[1][e] += w[e] * i1[e]; }
;                 }
; #pragma unroll
;                 for (int e = 0; e < 8; ++e) { ox[0][e] = silu_f(ox[0][e]); ox[1][e] = silu_f(ox[1][e]); }
	v_pk_fma_f32 v[124:125], v[114:115], v[134:135], v[124:125] op_sel_hi:[0,1,1]
	v_and_b32_e32 v135, 0xffff0000, v96
	v_mov_b32_e32 v134, v133
	s_waitcnt vmcnt(1)
	v_pk_fma_f32 v[124:125], v[118:119], v[130:131], v[124:125] op_sel_hi:[0,1,1]
	v_mul_f32_e32 v0, 0xbfb8aa3b, v124
	v_exp_f32_e32 v0, v0
	s_nop 0
	v_add_f32_e32 v0, 1.0, v0
	v_rcp_f32_e32 v130, v0
	v_mul_f32_e32 v0, 0xbfb8aa3b, v125
	v_exp_f32_e32 v0, v0
	s_nop 0
	v_add_f32_e32 v0, 1.0, v0
	v_rcp_f32_e32 v131, v0
	s_nop 0
	v_pk_mul_f32 v[124:125], v[124:125], v[130:131]
	v_and_b32_e32 v131, 0xffff0000, v88
	v_and_b32_e32 v130, 0xffff0000, v84
	v_mov_b32_e32 v132, v131
	v_pk_fma_f32 v[42:43], v[46:47], v[130:131], v[42:43] op_sel:[1,0,1]
	v_and_b32_e32 v47, 0xffff0000, v100
	v_pk_fma_f32 v[42:43], v[106:107], v[132:133], v[42:43] op_sel:[1,0,0]
	v_mov_b32_e32 v46, v135
	v_pk_fma_f32 v[42:43], v[110:111], v[134:135], v[42:43] op_sel:[1,0,0]
	v_and_b32_e32 v107, 0xffff0000, v104
	v_mov_b32_e32 v106, v47
	v_pk_fma_f32 v[42:43], v[114:115], v[46:47], v[42:43] op_sel:[1,0,0]
	v_lshlrev_b32_e32 v111, 16, v97
	v_pk_fma_f32 v[42:43], v[118:119], v[106:107], v[42:43] op_sel:[1,0,0]
	v_lshlrev_b32_e32 v107, 16, v93
	v_mul_f32_e32 v0, 0xbfb8aa3b, v42
	v_exp_f32_e32 v0, v0
	v_mov_b32_e32 v110, v107
	v_lshlrev_b32_e32 v115, 16, v101
	v_mov_b32_e32 v114, v111
	v_add_f32_e32 v0, 1.0, v0
	v_rcp_f32_e32 v46, v0
	v_mul_f32_e32 v0, 0xbfb8aa3b, v43
	v_exp_f32_e32 v0, v0
	s_nop 0
	v_add_f32_e32 v0, 1.0, v0
	v_rcp_f32_e32 v47, v0
	s_nop 0
	v_pk_mul_f32 v[42:43], v[42:43], v[46:47]
	v_lshlrev_b32_e32 v46, 16, v85
	v_lshlrev_b32_e32 v47, 16, v89
	v_mov_b32_e32 v106, v47
	v_pk_fma_f32 v[46:47], v[48:49], v[46:47], v[44:45] op_sel_hi:[0,1,0]
	v_pk_fma_f32 v[46:47], v[108:109], v[106:107], v[46:47] op_sel_hi:[0,1,1]
	v_pk_fma_f32 v[46:47], v[112:113], v[110:111], v[46:47] op_sel_hi:[0,1,1]
	v_lshlrev_b32_e32 v107, 16, v105
	v_mov_b32_e32 v106, v115
	v_pk_fma_f32 v[46:47], v[116:117], v[114:115], v[46:47] op_sel_hi:[0,1,1]
	v_pk_fma_f32 v[46:47], v[120:121], v[106:107], v[46:47] op_sel_hi:[0,1,1]
	v_mul_f32_e32 v0, 0xbfb8aa3b, v46
	v_exp_f32_e32 v0, v0
	v_mov_b32_e32 v44, v45
	v_and_b32_e32 v111, 0xffff0000, v93
	v_and_b32_e32 v115, 0xffff0000, v97
	v_add_f32_e32 v0, 1.0, v0
	v_rcp_f32_e32 v106, v0
	v_mul_f32_e32 v0, 0xbfb8aa3b, v47
	v_exp_f32_e32 v0, v0
	v_mov_b32_e32 v114, v111
	v_mov_b32_e32 v48, v115
	v_add_f32_e32 v0, 1.0, v0
	v_rcp_f32_e32 v107, v0
	v_mov_b32_e32 v0, v49
	v_and_b32_e32 v49, 0xffff0000, v101
	v_pk_mul_f32 v[46:47], v[46:47], v[106:107]
	v_and_b32_e32 v107, 0xffff0000, v89
	v_and_b32_e32 v106, 0xffff0000, v85
	v_mov_b32_e32 v110, v107
	v_pk_fma_f32 v[44:45], v[0:1], v[106:107], v[44:45] op_sel_hi:[0,1,0]
	v_mov_b32_e32 v0, v109
	v_pk_fma_f32 v[44:45], v[0:1], v[110:111], v[44:45] op_sel_hi:[0,1,1]
	v_mov_b32_e32 v0, v113
	v_pk_fma_f32 v[44:45], v[0:1], v[114:115], v[44:45] op_sel_hi:[0,1,1]
	v_mov_b32_e32 v0, v117
	v_and_b32_e32 v107, 0xffff0000, v105
	v_mov_b32_e32 v106, v49
	v_pk_fma_f32 v[44:45], v[0:1], v[48:49], v[44:45] op_sel_hi:[0,1,1]
	v_mov_b32_e32 v0, v121
	v_pk_fma_f32 v[44:45], v[0:1], v[106:107], v[44:45] op_sel_hi:[0,1,1]
	v_mul_f32_e32 v0, 0xbfb8aa3b, v44
	v_exp_f32_e32 v0, v0
	v_lshlrev_b32_e32 v107, 16, v90
	v_lshlrev_b32_e32 v109, 16, v94
	v_mov_b32_e32 v108, v107
	v_add_f32_e32 v0, 1.0, v0
	v_rcp_f32_e32 v48, v0
	v_mul_f32_e32 v0, 0xbfb8aa3b, v45
	v_exp_f32_e32 v0, v0
	v_lshlrev_b32_e32 v111, 16, v98
	v_mov_b32_e32 v110, v109
	v_add_f32_e32 v0, 1.0, v0
	v_rcp_f32_e32 v49, v0
	s_nop 0
	v_pk_mul_f32 v[44:45], v[44:45], v[48:49]
	v_lshlrev_b32_e32 v48, 16, v82
	v_lshlrev_b32_e32 v49, 16, v86
	v_mov_b32_e32 v106, v49
	v_pk_fma_f32 v[48:49], v[22:23], v[48:49], v[18:19] op_sel_hi:[0,1,0]
	v_pk_fma_f32 v[48:49], v[26:27], v[106:107], v[48:49] op_sel_hi:[0,1,1]
	v_pk_fma_f32 v[48:49], v[30:31], v[108:109], v[48:49] op_sel_hi:[0,1,1]
	v_lshlrev_b32_e32 v107, 16, v102
	v_mov_b32_e32 v106, v111
	v_pk_fma_f32 v[48:49], v[34:35], v[110:111], v[48:49] op_sel_hi:[0,1,1]
	s_waitcnt vmcnt(0)
	s_cmp_eq_u32 s90, 0
	s_cbranch_scc1 .Lssd_noflush
	buffer_store_dwordx4 v[222:225], v230, s[60:63], 0 offen sc1
	buffer_store_dwordx4 v[226:229], v231, s[60:63], 0 offen sc1
; __device__ __forceinline__ unsigned cvt_pk_bf16(float lo, float hi) { f32x2_t v = {lo, hi}; bf16x2_t b = __builtin_convertvector(v, bf16x2_t); return __builtin_bit_cast(unsigned, b); }
; #define LAS __attribute__((address_space(3)))
; __device__ __forceinline__ float silu_f(float x) { return x * __builtin_amdgcn_rcpf(1.f + __expf(-x)); }
; __device__ __forceinline__ void ssd_item(CArgs a, int layer, int item, LAS unsigned char* lds) {
;     ...
;                     for (int e = 0; e < 8; ++e) { ox[0][e] += w[e] * i0[e]; ox[1][e] += w[e] * i1[e]; }
;                 }
; #pragma unroll
;                 for (int e = 0; e < 8; ++e) { ox[0][e] = silu_f(ox[0][e]); ox[1][e] = silu_f(ox[1][e]); }
;             }
; #pragma unroll
;             for (int e = 0; e < 8; ++e) *(LAS unsigned*)(Xt + (xg * 8 + e) * SS_LD + xl0) = cvt_pk_bf16(ox[0][e], ox[1][e]);
;         }
;         if (cc + 1 < 16) SSD_PREFETCH(cc + 1);
.Lssd_noflush:
	s_nop 0
	s_cmp_eq_u32 s10, -1
	v_pk_fma_f32 v[48:49], v[38:39], v[106:107], v[48:49] op_sel_hi:[0,1,1]
	v_mul_f32_e32 v0, 0xbfb8aa3b, v48
	v_exp_f32_e32 v0, v0
	v_and_b32_e32 v109, 0xffff0000, v90
	v_and_b32_e32 v111, 0xffff0000, v94
	v_mov_b32_e32 v110, v109
	v_add_f32_e32 v0, 1.0, v0
	v_rcp_f32_e32 v106, v0
	v_mul_f32_e32 v0, 0xbfb8aa3b, v49
	v_exp_f32_e32 v0, v0
	s_nop 0
	v_add_f32_e32 v0, 1.0, v0
	v_rcp_f32_e32 v107, v0
	s_nop 0
	v_pk_mul_f32 v[48:49], v[48:49], v[106:107]
	v_and_b32_e32 v107, 0xffff0000, v86
	v_and_b32_e32 v106, 0xffff0000, v82
	v_mov_b32_e32 v108, v107
	v_pk_fma_f32 v[18:19], v[22:23], v[106:107], v[18:19] op_sel:[1,0,1]
	v_and_b32_e32 v23, 0xffff0000, v98
	v_pk_fma_f32 v[18:19], v[26:27], v[108:109], v[18:19] op_sel:[1,0,0]
	v_mov_b32_e32 v22, v111
	v_pk_fma_f32 v[18:19], v[30:31], v[110:111], v[18:19] op_sel:[1,0,0]
	v_and_b32_e32 v27, 0xffff0000, v102
	v_mov_b32_e32 v26, v23
	v_pk_fma_f32 v[18:19], v[34:35], v[22:23], v[18:19] op_sel:[1,0,0]
	v_lshlrev_b32_e32 v31, 16, v95
	v_pk_fma_f32 v[18:19], v[38:39], v[26:27], v[18:19] op_sel:[1,0,0]
	v_lshlrev_b32_e32 v27, 16, v91
	v_mul_f32_e32 v0, 0xbfb8aa3b, v18
	v_exp_f32_e32 v0, v0
	v_mov_b32_e32 v30, v27
	v_lshlrev_b32_e32 v35, 16, v99
	v_mov_b32_e32 v34, v31
	v_add_f32_e32 v0, 1.0, v0
	v_rcp_f32_e32 v22, v0
	v_mul_f32_e32 v0, 0xbfb8aa3b, v19
	v_exp_f32_e32 v0, v0
	s_nop 0
	v_add_f32_e32 v0, 1.0, v0
	v_rcp_f32_e32 v23, v0
	s_nop 0
	v_pk_mul_f32 v[18:19], v[18:19], v[22:23]
	v_lshlrev_b32_e32 v22, 16, v83
	v_lshlrev_b32_e32 v23, 16, v87
	v_mov_b32_e32 v26, v23
	v_pk_fma_f32 v[22:23], v[24:25], v[22:23], v[20:21] op_sel_hi:[0,1,0]
	v_pk_fma_f32 v[22:23], v[28:29], v[26:27], v[22:23] op_sel_hi:[0,1,1]
	v_pk_fma_f32 v[22:23], v[32:33], v[30:31], v[22:23] op_sel_hi:[0,1,1]
	v_lshlrev_b32_e32 v27, 16, v103
	v_mov_b32_e32 v26, v35
	v_pk_fma_f32 v[22:23], v[36:37], v[34:35], v[22:23] op_sel_hi:[0,1,1]
	v_pk_fma_f32 v[22:23], v[40:41], v[26:27], v[22:23] op_sel_hi:[0,1,1]
	v_mul_f32_e32 v0, 0xbfb8aa3b, v22
	v_exp_f32_e32 v0, v0
	v_mov_b32_e32 v20, v21
	v_and_b32_e32 v31, 0xffff0000, v91
	v_and_b32_e32 v35, 0xffff0000, v95
	v_add_f32_e32 v0, 1.0, v0
	v_rcp_f32_e32 v26, v0
	v_mul_f32_e32 v0, 0xbfb8aa3b, v23
	v_exp_f32_e32 v0, v0
	v_mov_b32_e32 v34, v31
	v_mov_b32_e32 v24, v35
	v_cvt_pk_bf16_f32 v18, v18, v19
	v_add_f32_e32 v0, 1.0, v0
	v_rcp_f32_e32 v27, v0
	v_mov_b32_e32 v0, v25
	v_and_b32_e32 v25, 0xffff0000, v99
	v_pk_mul_f32 v[22:23], v[22:23], v[26:27]
	v_and_b32_e32 v27, 0xffff0000, v87
	v_and_b32_e32 v26, 0xffff0000, v83
	v_mov_b32_e32 v30, v27
	v_pk_fma_f32 v[20:21], v[0:1], v[26:27], v[20:21] op_sel_hi:[0,1,0]
	v_mov_b32_e32 v0, v29
	v_pk_fma_f32 v[20:21], v[0:1], v[30:31], v[20:21] op_sel_hi:[0,1,1]
	v_mov_b32_e32 v0, v33
	v_pk_fma_f32 v[20:21], v[0:1], v[34:35], v[20:21] op_sel_hi:[0,1,1]
	v_mov_b32_e32 v0, v37
	v_and_b32_e32 v27, 0xffff0000, v103
	v_mov_b32_e32 v26, v25
	v_pk_fma_f32 v[20:21], v[0:1], v[24:25], v[20:21] op_sel_hi:[0,1,1]
	v_mov_b32_e32 v0, v41
	v_pk_fma_f32 v[20:21], v[0:1], v[26:27], v[20:21] op_sel_hi:[0,1,1]
	v_mul_f32_e32 v0, 0xbfb8aa3b, v20
	v_exp_f32_e32 v0, v0
	s_nop 0
	v_add_f32_e32 v0, 1.0, v0
	v_rcp_f32_e32 v24, v0
	v_mul_f32_e32 v0, 0xbfb8aa3b, v21
	v_exp_f32_e32 v0, v0
	s_nop 0
	v_add_f32_e32 v0, 1.0, v0
	v_rcp_f32_e32 v25, v0
	v_lshlrev_b32_e32 v0, 1, v127
	v_and_b32_e32 v0, -4, v0
	v_pk_mul_f32 v[20:21], v[20:21], v[24:25]
	v_mul_u32_u24_e32 v25, 0x110, v128
	v_cvt_pk_bf16_f32 v24, v124, v125
	v_add3_u32 v0, s38, v0, v25
	v_cvt_pk_bf16_f32 v25, v42, v43
	ds_write2_b32 v0, v24, v25 offset1:68
	v_cvt_pk_bf16_f32 v24, v46, v47
	v_cvt_pk_bf16_f32 v25, v44, v45
	ds_write2_b32 v0, v24, v25 offset0:136 offset1:204
	v_cvt_pk_bf16_f32 v24, v48, v49
	v_add_u32_e32 v0, 0x400, v0
	ds_write2_b32 v0, v24, v18 offset0:16 offset1:84
	v_cvt_pk_bf16_f32 v18, v22, v23
	v_cvt_pk_bf16_f32 v19, v20, v21
	ds_write2_b32 v0, v18, v19 offset0:152 offset1:220
	s_cbranch_scc1 .LBB0_207
	s_cmp_eq_u32 s10, 0
	s_cbranch_scc1 .Lssd_pf_slow
	v_mov_b32_e32 v42, v244
	s_and_b64 s[2:3], s[40:41], exec
	s_cselect_b32 s2, s26, s10
	v_ashrrev_i32_e32 v20, 2, v42
	s_lshl_b32 s27, s2, 7
	v_mov_b32_e32 v192, 0
	v_readfirstlane_b32 s3, v244
	s_cmp_lt_u32 s3, 0x80
	s_cbranch_scc0 .Lssd_nopdt
	v_add_u32_e32 v220, s27, v244
	v_lshlrev_b32_e32 v220, 7, v220
	global_load_dword v192, v220, s[16:17]
